# k-loops: one LDS-DMA piece after every MFMA (was every second) on the saddr form
# baseline (speedup 1.0000x reference)
.Lg0_top:
	s_waitcnt lgkmcnt(0)
	s_waitcnt vmcnt(0)
	s_barrier
	v_xor_b32_e32 v143, 0x10000, v143
	v_xor_b32_e32 v180, 0x10000, v180
	v_xor_b32_e32 v155, 0x10000, v155
	v_xor_b32_e32 v222, 0x10000, v222
	s_xor_b32 s87, s87, 0x10000
	ds_read_b128 v[156:159], v143
	ds_read_b128 v[160:163], v143 offset:2048
	ds_read_b128 v[164:167], v143 offset:4096
	ds_read_b128 v[168:171], v143 offset:6144
	ds_read_b128 v[190:193], v180 offset:32768
	ds_read_b128 v[194:197], v180 offset:34816
	ds_read_b128 v[198:201], v180 offset:36864
	ds_read_b128 v[202:205], v180 offset:38912
	v_mfma_f32_16x16x32_bf16 v[60:63], v[172:175], v[206:209], v[60:63]
	s_mov_b32 m0, s87
	s_add_u32 s88, s60, s16
	s_addc_u32 s89, s61, s17
	global_load_lds_dwordx4 v144, s[88:89]
	v_mfma_f32_16x16x32_bf16 v[52:55], v[172:175], v[210:213], v[52:55]
	s_add_u32 m0, s87, 0x2000
	s_add_u32 s88, s60, s18
	s_addc_u32 s89, s61, s19
	global_load_lds_dwordx4 v144, s[88:89]
	v_mfma_f32_16x16x32_bf16 v[56:59], v[172:175], v[214:217], v[56:59]
	s_add_u32 m0, s87, 0x4000
	s_add_u32 s88, s60, s22
	s_addc_u32 s89, s61, s23
	global_load_lds_dwordx4 v144, s[88:89]
	v_mfma_f32_16x16x32_bf16 v[48:51], v[172:175], v[218:221], v[48:51]
	s_add_u32 m0, s87, 0x6000
	s_add_u32 s88, s60, s40
	s_addc_u32 s89, s61, s41
	global_load_lds_dwordx4 v144, s[88:89]
	v_mfma_f32_16x16x32_bf16 v[44:47], v[176:179], v[206:209], v[44:47]
	s_add_u32 m0, s87, 0x8000
	s_add_u32 s88, s60, s42
	s_addc_u32 s89, s61, s43
	global_load_lds_dwordx4 v145, s[88:89]
	v_mfma_f32_16x16x32_bf16 v[36:39], v[176:179], v[210:213], v[36:39]
	s_add_u32 m0, s87, 0xa000
	s_add_u32 s88, s60, s52
	s_addc_u32 s89, s61, s53
	global_load_lds_dwordx4 v145, s[88:89]
	v_mfma_f32_16x16x32_bf16 v[40:43], v[176:179], v[214:217], v[40:43]
	s_add_u32 m0, s87, 0xc000
	s_add_u32 s88, s60, s54
	s_addc_u32 s89, s61, s55
	global_load_lds_dwordx4 v145, s[88:89]
	v_mfma_f32_16x16x32_bf16 v[32:35], v[176:179], v[218:221], v[32:35]
	s_add_u32 m0, s87, 0xe000
	s_add_u32 s88, s60, s56
	s_addc_u32 s89, s61, s57
	global_load_lds_dwordx4 v145, s[88:89]
	v_mfma_f32_16x16x32_bf16 v[28:31], v[182:185], v[206:209], v[28:31]
	v_mfma_f32_16x16x32_bf16 v[16:19], v[182:185], v[210:213], v[16:19]
	v_mfma_f32_16x16x32_bf16 v[24:27], v[182:185], v[214:217], v[24:27]
	v_mfma_f32_16x16x32_bf16 v[12:15], v[182:185], v[218:221], v[12:15]
	v_mfma_f32_16x16x32_bf16 v[4:7], v[186:189], v[206:209], v[4:7]
	v_mfma_f32_16x16x32_bf16 v[0:3], v[186:189], v[210:213], v[0:3]
	v_mfma_f32_16x16x32_bf16 v[20:23], v[186:189], v[214:217], v[20:23]
	v_mfma_f32_16x16x32_bf16 v[8:11], v[186:189], v[218:221], v[8:11]

.Lg1_top:
	s_waitcnt lgkmcnt(0)
	s_waitcnt vmcnt(0)
	s_barrier
	v_xor_b32_e32 v141, 0x10000, v141
	v_xor_b32_e32 v210, 0x10000, v210
	v_xor_b32_e32 v180, 0x10000, v180
	v_xor_b32_e32 v211, 0x10000, v211
	s_xor_b32 s59, s59, 0x10000
	ds_read_b128 v[142:145], v141
	ds_read_b128 v[146:149], v141 offset:2048
	ds_read_b128 v[150:153], v141 offset:4096
	ds_read_b128 v[154:157], v141 offset:6144
	ds_read_b128 v[174:177], v210 offset:32768
	ds_read_b128 v[182:185], v210 offset:34816
	ds_read_b128 v[186:189], v210 offset:36864
	ds_read_b128 v[190:193], v210 offset:38912
	v_mfma_f32_16x16x32_bf16 v[60:63], v[158:161], v[194:197], v[60:63]
	s_mov_b32 m0, s59
	s_add_u32 s52, s50, s14
	s_addc_u32 s53, s51, s15
	global_load_lds_dwordx4 v178, s[52:53]
	v_mfma_f32_16x16x32_bf16 v[56:59], v[158:161], v[198:201], v[56:59]
	s_add_u32 m0, s59, 0x2000
	s_add_u32 s52, s50, s16
	s_addc_u32 s53, s51, s17
	global_load_lds_dwordx4 v178, s[52:53]
	v_mfma_f32_16x16x32_bf16 v[52:55], v[158:161], v[202:205], v[52:55]
	s_add_u32 m0, s59, 0x4000
	s_add_u32 s52, s50, s18
	s_addc_u32 s53, s51, s19
	global_load_lds_dwordx4 v178, s[52:53]
	v_mfma_f32_16x16x32_bf16 v[48:51], v[158:161], v[206:209], v[48:51]
	s_add_u32 m0, s59, 0x6000
	s_add_u32 s52, s50, s22
	s_addc_u32 s53, s51, s23
	global_load_lds_dwordx4 v178, s[52:53]
	v_mfma_f32_16x16x32_bf16 v[44:47], v[162:165], v[194:197], v[44:47]
	s_add_u32 m0, s59, 0x8000
	s_add_u32 s52, s50, s40
	s_addc_u32 s53, s51, s41
	global_load_lds_dwordx4 v179, s[52:53]
	v_mfma_f32_16x16x32_bf16 v[40:43], v[162:165], v[198:201], v[40:43]
	s_add_u32 m0, s59, 0xa000
	s_add_u32 s52, s50, s42
	s_addc_u32 s53, s51, s43
	global_load_lds_dwordx4 v179, s[52:53]
	v_mfma_f32_16x16x32_bf16 v[36:39], v[162:165], v[202:205], v[36:39]
	s_add_u32 m0, s59, 0xc000
	s_add_u32 s52, s50, s44
	s_addc_u32 s53, s51, s45
	global_load_lds_dwordx4 v179, s[52:53]
	v_mfma_f32_16x16x32_bf16 v[32:35], v[162:165], v[206:209], v[32:35]
	s_add_u32 m0, s59, 0xe000
	s_add_u32 s52, s50, s46
	s_addc_u32 s53, s51, s47
	global_load_lds_dwordx4 v179, s[52:53]
	v_mfma_f32_16x16x32_bf16 v[28:31], v[166:169], v[194:197], v[28:31]
	v_mfma_f32_16x16x32_bf16 v[20:23], v[166:169], v[198:201], v[20:23]
	v_mfma_f32_16x16x32_bf16 v[16:19], v[166:169], v[202:205], v[16:19]
	v_mfma_f32_16x16x32_bf16 v[8:11], v[166:169], v[206:209], v[8:11]
	v_mfma_f32_16x16x32_bf16 v[4:7], v[170:173], v[194:197], v[4:7]
	v_mfma_f32_16x16x32_bf16 v[0:3], v[170:173], v[198:201], v[0:3]
	v_mfma_f32_16x16x32_bf16 v[24:27], v[170:173], v[202:205], v[24:27]
	v_mfma_f32_16x16x32_bf16 v[12:15], v[170:173], v[206:209], v[12:15]

.Lg2_top:
	s_waitcnt lgkmcnt(0)
	s_waitcnt vmcnt(0)
	s_barrier
	v_xor_b32_e32 v180, 0x10000, v180
	v_xor_b32_e32 v215, 0x10000, v215
	v_xor_b32_e32 v214, 0x10000, v214
	v_xor_b32_e32 v216, 0x10000, v216
	s_xor_b32 s62, s62, 0x10000
	ds_read_b128 v[146:149], v180
	ds_read_b128 v[150:153], v180 offset:2048
	ds_read_b128 v[154:157], v180 offset:4096
	ds_read_b128 v[158:161], v180 offset:6144
	ds_read_b128 v[182:185], v215 offset:32768
	ds_read_b128 v[186:189], v215 offset:34816
	ds_read_b128 v[190:193], v215 offset:36864
	ds_read_b128 v[194:197], v215 offset:38912
	v_mfma_f32_16x16x32_bf16 v[60:63], v[162:165], v[198:201], v[60:63]
	s_mov_b32 m0, s62
	s_add_u32 s50, s48, s12
	s_addc_u32 s51, s49, s13
	global_load_lds_dwordx4 v178, s[50:51]
	v_mfma_f32_16x16x32_bf16 v[56:59], v[162:165], v[202:205], v[56:59]
	s_add_u32 m0, s62, 0x2000
	s_add_u32 s50, s48, s14
	s_addc_u32 s51, s49, s15
	global_load_lds_dwordx4 v178, s[50:51]
	v_mfma_f32_16x16x32_bf16 v[52:55], v[162:165], v[206:209], v[52:55]
	s_add_u32 m0, s62, 0x4000
	s_add_u32 s50, s48, s16
	s_addc_u32 s51, s49, s17
	global_load_lds_dwordx4 v178, s[50:51]
	v_mfma_f32_16x16x32_bf16 v[44:47], v[162:165], v[210:213], v[44:47]
	s_add_u32 m0, s62, 0x6000
	s_add_u32 s50, s48, s18
	s_addc_u32 s51, s49, s19
	global_load_lds_dwordx4 v178, s[50:51]
	v_mfma_f32_16x16x32_bf16 v[36:39], v[166:169], v[198:201], v[36:39]
	s_add_u32 m0, s62, 0x8000
	s_add_u32 s50, s48, s22
	s_addc_u32 s51, s49, s23
	global_load_lds_dwordx4 v179, s[50:51]
	v_mfma_f32_16x16x32_bf16 v[32:35], v[166:169], v[202:205], v[32:35]
	s_add_u32 m0, s62, 0xa000
	s_add_u32 s50, s48, s36
	s_addc_u32 s51, s49, s37
	global_load_lds_dwordx4 v179, s[50:51]
	v_mfma_f32_16x16x32_bf16 v[28:31], v[166:169], v[206:209], v[28:31]
	s_add_u32 m0, s62, 0xc000
	s_add_u32 s50, s48, s40
	s_addc_u32 s51, s49, s41
	global_load_lds_dwordx4 v179, s[50:51]
	v_mfma_f32_16x16x32_bf16 v[24:27], v[166:169], v[210:213], v[24:27]
	s_add_u32 m0, s62, 0xe000
	s_add_u32 s50, s48, s42
	s_addc_u32 s51, s49, s43
	global_load_lds_dwordx4 v179, s[50:51]
	v_mfma_f32_16x16x32_bf16 v[20:23], v[170:173], v[198:201], v[20:23]
	v_mfma_f32_16x16x32_bf16 v[16:19], v[170:173], v[202:205], v[16:19]
	v_mfma_f32_16x16x32_bf16 v[12:15], v[170:173], v[206:209], v[12:15]
	v_mfma_f32_16x16x32_bf16 v[8:11], v[170:173], v[210:213], v[8:11]
	v_mfma_f32_16x16x32_bf16 v[4:7], v[174:177], v[198:201], v[4:7]
	v_mfma_f32_16x16x32_bf16 v[0:3], v[174:177], v[202:205], v[0:3]
	v_mfma_f32_16x16x32_bf16 v[48:51], v[174:177], v[206:209], v[48:51]
	v_mfma_f32_16x16x32_bf16 v[40:43], v[174:177], v[210:213], v[40:43]

.Lg5_top:
	s_waitcnt lgkmcnt(0)
	s_waitcnt vmcnt(0)
	s_barrier
	v_xor_b32_e32 v180, 0x10000, v180
	v_xor_b32_e32 v245, 0x10000, v245
	v_xor_b32_e32 v244, 0x10000, v244
	v_xor_b32_e32 v246, 0x10000, v246
	s_xor_b32 s87, s87, 0x10000
	ds_read_b128 v[176:179], v180
	ds_read_b128 v[182:185], v180 offset:2048
	ds_read_b128 v[186:189], v180 offset:4096
	ds_read_b128 v[190:193], v180 offset:6144
	ds_read_b128 v[210:213], v245 offset:32768
	ds_read_b128 v[214:217], v245 offset:34816
	ds_read_b128 v[218:221], v245 offset:36864
	ds_read_b128 v[222:225], v245 offset:38912
	v_mfma_f32_16x16x32_bf16 v[60:63], v[194:197], v[226:229], v[60:63]
	s_mov_b32 m0, s87
	s_add_u32 s70, s68, 0x4000080
	s_addc_u32 s71, s69, 0
	global_load_lds_dwordx4 v242, s[70:71]
	v_mfma_f32_16x16x32_bf16 v[56:59], v[194:197], v[230:233], v[56:59]
	s_add_u32 m0, s87, 0x2000
	s_add_u32 s70, s68, 0x4020080
	s_addc_u32 s71, s69, 0
	global_load_lds_dwordx4 v242, s[70:71]
	v_mfma_f32_16x16x32_bf16 v[52:55], v[194:197], v[234:237], v[52:55]
	s_add_u32 m0, s87, 0x4000
	s_add_u32 s70, s68, 0x4040080
	s_addc_u32 s71, s69, 0
	global_load_lds_dwordx4 v242, s[70:71]
	v_mfma_f32_16x16x32_bf16 v[48:51], v[194:197], v[238:241], v[48:51]
	s_add_u32 m0, s87, 0x6000
	s_add_u32 s70, s68, s14
	s_addc_u32 s71, s69, s15
	global_load_lds_dwordx4 v242, s[70:71]
	v_mfma_f32_16x16x32_bf16 v[44:47], v[198:201], v[226:229], v[44:47]
	s_add_u32 m0, s87, 0x8000
	s_add_u32 s70, s68, s16
	s_addc_u32 s71, s69, s17
	global_load_lds_dwordx4 v243, s[70:71]
	v_mfma_f32_16x16x32_bf16 v[40:43], v[198:201], v[230:233], v[40:43]
	s_add_u32 m0, s87, 0xa000
	s_add_u32 s70, s68, s18
	s_addc_u32 s71, s69, s19
	global_load_lds_dwordx4 v243, s[70:71]
	v_mfma_f32_16x16x32_bf16 v[36:39], v[198:201], v[234:237], v[36:39]
	s_add_u32 m0, s87, 0xc000
	s_add_u32 s70, s68, s22
	s_addc_u32 s71, s69, s23
	global_load_lds_dwordx4 v243, s[70:71]
	v_mfma_f32_16x16x32_bf16 v[32:35], v[198:201], v[238:241], v[32:35]
	s_add_u32 m0, s87, 0xe000
	s_add_u32 s70, s68, s36
	s_addc_u32 s71, s69, s37
	global_load_lds_dwordx4 v243, s[70:71]
	v_mfma_f32_16x16x32_bf16 v[28:31], v[202:205], v[226:229], v[28:31]
	v_mfma_f32_16x16x32_bf16 v[24:27], v[202:205], v[230:233], v[24:27]
	v_mfma_f32_16x16x32_bf16 v[20:23], v[202:205], v[234:237], v[20:23]
	v_mfma_f32_16x16x32_bf16 v[16:19], v[202:205], v[238:241], v[16:19]
	v_mfma_f32_16x16x32_bf16 v[8:11], v[206:209], v[226:229], v[8:11]
	v_mfma_f32_16x16x32_bf16 v[0:3], v[206:209], v[230:233], v[0:3]
	v_mfma_f32_16x16x32_bf16 v[12:15], v[206:209], v[234:237], v[12:15]
	v_mfma_f32_16x16x32_bf16 v[4:7], v[206:209], v[238:241], v[4:7]

.Lg6_top:
	s_waitcnt lgkmcnt(0)
	s_waitcnt vmcnt(0)
	s_barrier
	v_xor_b32_e32 v180, 0x10000, v180
	v_xor_b32_e32 v249, 0x10000, v249
	v_xor_b32_e32 v248, 0x10000, v248
	v_xor_b32_e32 v250, 0x10000, v250
	s_xor_b32 s69, s69, 0x10000
	ds_read_b128 v[182:185], v180
	ds_read_b128 v[186:189], v180 offset:2048
	ds_read_b128 v[190:193], v180 offset:4096
	ds_read_b128 v[194:197], v180 offset:6144
	ds_read_b128 v[214:217], v249 offset:32768
	ds_read_b128 v[218:221], v249 offset:34816
	ds_read_b128 v[222:225], v249 offset:36864
	ds_read_b128 v[226:229], v249 offset:38912
	v_mfma_f32_16x16x32_bf16 v[60:63], v[198:201], v[230:233], v[60:63]
	s_mov_b32 m0, s69
	s_add_u32 s66, s64, s44
	s_addc_u32 s67, s65, s45
	global_load_lds_dwordx4 v246, s[66:67]
	v_mfma_f32_16x16x32_bf16 v[56:59], v[198:201], v[234:237], v[56:59]
	s_add_u32 m0, s69, 0x2000
	s_add_u32 s66, s64, s46
	s_addc_u32 s67, s65, s47
	global_load_lds_dwordx4 v246, s[66:67]
	v_mfma_f32_16x16x32_bf16 v[52:55], v[198:201], v[238:241], v[52:55]
	s_add_u32 m0, s69, 0x4000
	s_add_u32 s66, s64, s48
	s_addc_u32 s67, s65, s49
	global_load_lds_dwordx4 v246, s[66:67]
	v_mfma_f32_16x16x32_bf16 v[48:51], v[198:201], v[242:245], v[48:51]
	s_add_u32 m0, s69, 0x6000
	s_add_u32 s66, s64, s50
	s_addc_u32 s67, s65, s51
	global_load_lds_dwordx4 v246, s[66:67]
	v_mfma_f32_16x16x32_bf16 v[44:47], v[202:205], v[230:233], v[44:47]
	s_add_u32 m0, s69, 0x8000
	s_add_u32 s66, s64, s52
	s_addc_u32 s67, s65, s53
	global_load_lds_dwordx4 v247, s[66:67]
	v_mfma_f32_16x16x32_bf16 v[40:43], v[202:205], v[234:237], v[40:43]
	s_add_u32 m0, s69, 0xa000
	s_add_u32 s66, s64, s54
	s_addc_u32 s67, s65, s55
	global_load_lds_dwordx4 v247, s[66:67]
	v_mfma_f32_16x16x32_bf16 v[36:39], v[202:205], v[238:241], v[36:39]
	s_add_u32 m0, s69, 0xc000
	s_add_u32 s66, s64, s60
	s_addc_u32 s67, s65, s61
	global_load_lds_dwordx4 v247, s[66:67]
	v_mfma_f32_16x16x32_bf16 v[32:35], v[202:205], v[242:245], v[32:35]
	s_add_u32 m0, s69, 0xe000
	s_add_u32 s66, s64, s62
	s_addc_u32 s67, s65, s63
	global_load_lds_dwordx4 v247, s[66:67]
	v_mfma_f32_16x16x32_bf16 v[28:31], v[206:209], v[230:233], v[28:31]
	v_mfma_f32_16x16x32_bf16 v[24:27], v[206:209], v[234:237], v[24:27]
	v_mfma_f32_16x16x32_bf16 v[20:23], v[206:209], v[238:241], v[20:23]
	v_mfma_f32_16x16x32_bf16 v[16:19], v[206:209], v[242:245], v[16:19]
	v_mfma_f32_16x16x32_bf16 v[12:15], v[210:213], v[230:233], v[12:15]
	v_mfma_f32_16x16x32_bf16 v[0:3], v[210:213], v[234:237], v[0:3]
	v_mfma_f32_16x16x32_bf16 v[8:11], v[210:213], v[238:241], v[8:11]
	v_mfma_f32_16x16x32_bf16 v[4:7], v[210:213], v[242:245], v[4:7]

.Lg7_top:
	s_waitcnt lgkmcnt(0)
	s_waitcnt vmcnt(0)
	s_barrier
	v_xor_b32_e32 v141, 0x10000, v141
	v_xor_b32_e32 v210, 0x10000, v210
	v_xor_b32_e32 v180, 0x10000, v180
	v_xor_b32_e32 v211, 0x10000, v211
	s_xor_b32 s61, s61, 0x10000
	ds_read_b128 v[142:145], v141
	ds_read_b128 v[146:149], v141 offset:2048
	ds_read_b128 v[150:153], v141 offset:4096
	ds_read_b128 v[154:157], v141 offset:6144
	ds_read_b128 v[174:177], v210 offset:32768
	ds_read_b128 v[182:185], v210 offset:34816
	ds_read_b128 v[186:189], v210 offset:36864
	ds_read_b128 v[190:193], v210 offset:38912
	v_mfma_f32_16x16x32_bf16 v[60:63], v[158:161], v[194:197], v[60:63]
	s_mov_b32 m0, s61
	s_add_u32 s50, s48, s14
	s_addc_u32 s51, s49, s15
	global_load_lds_dwordx4 v178, s[50:51]
	v_mfma_f32_16x16x32_bf16 v[56:59], v[158:161], v[198:201], v[56:59]
	s_add_u32 m0, s61, 0x2000
	s_add_u32 s50, s48, s16
	s_addc_u32 s51, s49, s17
	global_load_lds_dwordx4 v178, s[50:51]
	v_mfma_f32_16x16x32_bf16 v[52:55], v[158:161], v[202:205], v[52:55]
	s_add_u32 m0, s61, 0x4000
	s_add_u32 s50, s48, s18
	s_addc_u32 s51, s49, s19
	global_load_lds_dwordx4 v178, s[50:51]
	v_mfma_f32_16x16x32_bf16 v[48:51], v[158:161], v[206:209], v[48:51]
	s_add_u32 m0, s61, 0x6000
	s_add_u32 s50, s48, s22
	s_addc_u32 s51, s49, s23
	global_load_lds_dwordx4 v178, s[50:51]
	v_mfma_f32_16x16x32_bf16 v[44:47], v[162:165], v[194:197], v[44:47]
	s_add_u32 m0, s61, 0x8000
	s_add_u32 s50, s48, s36
	s_addc_u32 s51, s49, s37
	global_load_lds_dwordx4 v179, s[50:51]
	v_mfma_f32_16x16x32_bf16 v[32:35], v[162:165], v[198:201], v[32:35]
	s_add_u32 m0, s61, 0xa000
	s_add_u32 s50, s48, s40
	s_addc_u32 s51, s49, s41
	global_load_lds_dwordx4 v179, s[50:51]
	v_mfma_f32_16x16x32_bf16 v[28:31], v[162:165], v[202:205], v[28:31]
	s_add_u32 m0, s61, 0xc000
	s_add_u32 s50, s48, s42
	s_addc_u32 s51, s49, s43
	global_load_lds_dwordx4 v179, s[50:51]
	v_mfma_f32_16x16x32_bf16 v[24:27], v[162:165], v[206:209], v[24:27]
	s_add_u32 m0, s61, 0xe000
	s_add_u32 s50, s48, s44
	s_addc_u32 s51, s49, s45
	global_load_lds_dwordx4 v179, s[50:51]
	v_mfma_f32_16x16x32_bf16 v[20:23], v[166:169], v[194:197], v[20:23]
	v_mfma_f32_16x16x32_bf16 v[16:19], v[166:169], v[198:201], v[16:19]
	v_mfma_f32_16x16x32_bf16 v[12:15], v[166:169], v[202:205], v[12:15]
	v_mfma_f32_16x16x32_bf16 v[8:11], v[166:169], v[206:209], v[8:11]
	v_mfma_f32_16x16x32_bf16 v[4:7], v[170:173], v[194:197], v[4:7]
	v_mfma_f32_16x16x32_bf16 v[0:3], v[170:173], v[198:201], v[0:3]
	v_mfma_f32_16x16x32_bf16 v[40:43], v[170:173], v[202:205], v[40:43]
	v_mfma_f32_16x16x32_bf16 v[36:39], v[170:173], v[206:209], v[36:39]

.Lg8_top:
	s_waitcnt lgkmcnt(0)
	s_waitcnt vmcnt(0)
	s_barrier
	v_xor_b32_e32 v180, 0x10000, v180
	v_xor_b32_e32 v223, 0x10000, v223
	v_xor_b32_e32 v222, 0x10000, v222
	v_xor_b32_e32 v224, 0x10000, v224
	s_xor_b32 s59, s59, 0x10000
	ds_read_b128 v[154:157], v180
	ds_read_b128 v[158:161], v180 offset:2048
	ds_read_b128 v[162:165], v180 offset:4096
	ds_read_b128 v[166:169], v180 offset:6144
	ds_read_b128 v[190:193], v223 offset:32768
	ds_read_b128 v[194:197], v223 offset:34816
	ds_read_b128 v[198:201], v223 offset:36864
	ds_read_b128 v[202:205], v223 offset:38912
	v_mfma_f32_16x16x32_bf16 v[60:63], v[170:173], v[206:209], v[60:63]
	s_mov_b32 m0, s59
	s_add_u32 s62, s60, s22
	s_addc_u32 s63, s61, s23
	global_load_lds_dwordx4 v178, s[62:63]
	v_mfma_f32_16x16x32_bf16 v[56:59], v[170:173], v[210:213], v[56:59]
	s_add_u32 m0, s59, 0x2000
	s_add_u32 s62, s60, s36
	s_addc_u32 s63, s61, s37
	global_load_lds_dwordx4 v178, s[62:63]
	v_mfma_f32_16x16x32_bf16 v[52:55], v[170:173], v[214:217], v[52:55]
	s_add_u32 m0, s59, 0x4000
	s_add_u32 s62, s60, s38
	s_addc_u32 s63, s61, s39
	global_load_lds_dwordx4 v178, s[62:63]
	v_mfma_f32_16x16x32_bf16 v[44:47], v[170:173], v[218:221], v[44:47]
	s_add_u32 m0, s59, 0x6000
	s_add_u32 s62, s60, s40
	s_addc_u32 s63, s61, s41
	global_load_lds_dwordx4 v178, s[62:63]
	v_mfma_f32_16x16x32_bf16 v[36:39], v[174:177], v[206:209], v[36:39]
	s_add_u32 m0, s59, 0x8000
	s_add_u32 s62, s60, s42
	s_addc_u32 s63, s61, s43
	global_load_lds_dwordx4 v179, s[62:63]
	v_mfma_f32_16x16x32_bf16 v[32:35], v[174:177], v[210:213], v[32:35]
	s_add_u32 m0, s59, 0xa000
	s_add_u32 s62, s60, s44
	s_addc_u32 s63, s61, s45
	global_load_lds_dwordx4 v179, s[62:63]
	v_mfma_f32_16x16x32_bf16 v[28:31], v[174:177], v[214:217], v[28:31]
	s_add_u32 m0, s59, 0xc000
	s_add_u32 s62, s60, s46
	s_addc_u32 s63, s61, s47
	global_load_lds_dwordx4 v179, s[62:63]
	v_mfma_f32_16x16x32_bf16 v[24:27], v[174:177], v[218:221], v[24:27]
	s_add_u32 m0, s59, 0xe000
	s_add_u32 s62, s60, s48
	s_addc_u32 s63, s61, s49
	global_load_lds_dwordx4 v179, s[62:63]
	v_mfma_f32_16x16x32_bf16 v[20:23], v[182:185], v[206:209], v[20:23]
	v_mfma_f32_16x16x32_bf16 v[16:19], v[182:185], v[210:213], v[16:19]
	v_mfma_f32_16x16x32_bf16 v[12:15], v[182:185], v[214:217], v[12:15]
	v_mfma_f32_16x16x32_bf16 v[8:11], v[182:185], v[218:221], v[8:11]
	v_mfma_f32_16x16x32_bf16 v[4:7], v[186:189], v[206:209], v[4:7]
	v_mfma_f32_16x16x32_bf16 v[0:3], v[186:189], v[210:213], v[0:3]
	v_mfma_f32_16x16x32_bf16 v[48:51], v[186:189], v[214:217], v[48:51]
	v_mfma_f32_16x16x32_bf16 v[40:43], v[186:189], v[218:221], v[40:43]

.Lg9_top:
	s_waitcnt lgkmcnt(0)
	s_waitcnt vmcnt(0)
	s_barrier
	v_xor_b32_e32 v141, 0x10000, v141
	v_xor_b32_e32 v210, 0x10000, v210
	v_xor_b32_e32 v180, 0x10000, v180
	v_xor_b32_e32 v211, 0x10000, v211
	s_xor_b32 s59, s59, 0x10000
	ds_read_b128 v[142:145], v141
	ds_read_b128 v[146:149], v141 offset:2048
	ds_read_b128 v[150:153], v141 offset:4096
	ds_read_b128 v[154:157], v141 offset:6144
	ds_read_b128 v[174:177], v210 offset:32768
	ds_read_b128 v[182:185], v210 offset:34816
	ds_read_b128 v[186:189], v210 offset:36864
	ds_read_b128 v[190:193], v210 offset:38912
	v_mfma_f32_16x16x32_bf16 v[60:63], v[158:161], v[194:197], v[60:63]
	s_mov_b32 m0, s59
	s_add_u32 s46, s44, s12
	s_addc_u32 s47, s45, s13
	global_load_lds_dwordx4 v178, s[46:47]
	v_mfma_f32_16x16x32_bf16 v[56:59], v[158:161], v[198:201], v[56:59]
	s_add_u32 m0, s59, 0x2000
	s_add_u32 s46, s44, s14
	s_addc_u32 s47, s45, s15
	global_load_lds_dwordx4 v178, s[46:47]
	v_mfma_f32_16x16x32_bf16 v[52:55], v[158:161], v[202:205], v[52:55]
	s_add_u32 m0, s59, 0x4000
	s_add_u32 s46, s44, s16
	s_addc_u32 s47, s45, s17
	global_load_lds_dwordx4 v178, s[46:47]
	v_mfma_f32_16x16x32_bf16 v[48:51], v[158:161], v[206:209], v[48:51]
	s_add_u32 m0, s59, 0x6000
	s_add_u32 s46, s44, s18
	s_addc_u32 s47, s45, s19
	global_load_lds_dwordx4 v178, s[46:47]
	v_mfma_f32_16x16x32_bf16 v[44:47], v[162:165], v[194:197], v[44:47]
	s_add_u32 m0, s59, 0x8000
	s_add_u32 s46, s44, s22
	s_addc_u32 s47, s45, s23
	global_load_lds_dwordx4 v179, s[46:47]
	v_mfma_f32_16x16x32_bf16 v[32:35], v[162:165], v[198:201], v[32:35]
	s_add_u32 m0, s59, 0xa000
	s_add_u32 s46, s44, s36
	s_addc_u32 s47, s45, s37
	global_load_lds_dwordx4 v179, s[46:47]
	v_mfma_f32_16x16x32_bf16 v[28:31], v[162:165], v[202:205], v[28:31]
	s_add_u32 m0, s59, 0xc000
	s_add_u32 s46, s44, s38
	s_addc_u32 s47, s45, s39
	global_load_lds_dwordx4 v179, s[46:47]
	v_mfma_f32_16x16x32_bf16 v[24:27], v[162:165], v[206:209], v[24:27]
	s_add_u32 m0, s59, 0xe000
	s_add_u32 s46, s44, s40
	s_addc_u32 s47, s45, s41
	global_load_lds_dwordx4 v179, s[46:47]
	v_mfma_f32_16x16x32_bf16 v[20:23], v[166:169], v[194:197], v[20:23]
	v_mfma_f32_16x16x32_bf16 v[16:19], v[166:169], v[198:201], v[16:19]
	v_mfma_f32_16x16x32_bf16 v[12:15], v[166:169], v[202:205], v[12:15]
	v_mfma_f32_16x16x32_bf16 v[8:11], v[166:169], v[206:209], v[8:11]
	v_mfma_f32_16x16x32_bf16 v[4:7], v[170:173], v[194:197], v[4:7]
	v_mfma_f32_16x16x32_bf16 v[0:3], v[170:173], v[198:201], v[0:3]
	v_mfma_f32_16x16x32_bf16 v[40:43], v[170:173], v[202:205], v[40:43]
	v_mfma_f32_16x16x32_bf16 v[36:39], v[170:173], v[206:209], v[36:39]

.Lg10_top:
	s_waitcnt lgkmcnt(0)
	s_waitcnt vmcnt(0)
	s_barrier
	v_xor_b32_e32 v143, 0x10000, v143
	v_xor_b32_e32 v180, 0x10000, v180
	v_xor_b32_e32 v155, 0x10000, v155
	v_xor_b32_e32 v222, 0x10000, v222
	s_xor_b32 s57, s57, 0x10000
	ds_read_b128 v[156:159], v143
	ds_read_b128 v[160:163], v143 offset:2048
	ds_read_b128 v[164:167], v143 offset:4096
	ds_read_b128 v[168:171], v143 offset:6144
	ds_read_b128 v[190:193], v180 offset:32768
	ds_read_b128 v[194:197], v180 offset:34816
	ds_read_b128 v[198:201], v180 offset:36864
	ds_read_b128 v[202:205], v180 offset:38912
	v_mfma_f32_16x16x32_bf16 v[60:63], v[172:175], v[206:209], v[60:63]
	s_mov_b32 m0, s57
	s_add_u32 s46, s44, s14
	s_addc_u32 s47, s45, s15
	global_load_lds_dwordx4 v144, s[46:47]
	v_mfma_f32_16x16x32_bf16 v[52:55], v[172:175], v[210:213], v[52:55]
	s_add_u32 m0, s57, 0x2000
	s_add_u32 s46, s44, s16
	s_addc_u32 s47, s45, s17
	global_load_lds_dwordx4 v144, s[46:47]
	v_mfma_f32_16x16x32_bf16 v[56:59], v[172:175], v[214:217], v[56:59]
	s_add_u32 m0, s57, 0x4000
	s_add_u32 s46, s44, s18
	s_addc_u32 s47, s45, s19
	global_load_lds_dwordx4 v144, s[46:47]
	v_mfma_f32_16x16x32_bf16 v[48:51], v[172:175], v[218:221], v[48:51]
	s_add_u32 m0, s57, 0x6000
	s_add_u32 s46, s44, s22
	s_addc_u32 s47, s45, s23
	global_load_lds_dwordx4 v144, s[46:47]
	v_mfma_f32_16x16x32_bf16 v[44:47], v[176:179], v[206:209], v[44:47]
	s_add_u32 m0, s57, 0x8000
	s_add_u32 s46, s44, s30
	s_addc_u32 s47, s45, s31
	global_load_lds_dwordx4 v145, s[46:47]
	v_mfma_f32_16x16x32_bf16 v[36:39], v[176:179], v[210:213], v[36:39]
	s_add_u32 m0, s57, 0xa000
	s_add_u32 s46, s44, s36
	s_addc_u32 s47, s45, s37
	global_load_lds_dwordx4 v145, s[46:47]
	v_mfma_f32_16x16x32_bf16 v[40:43], v[176:179], v[214:217], v[40:43]
	s_add_u32 m0, s57, 0xc000
	s_add_u32 s46, s44, s38
	s_addc_u32 s47, s45, s39
	global_load_lds_dwordx4 v145, s[46:47]
	v_mfma_f32_16x16x32_bf16 v[32:35], v[176:179], v[218:221], v[32:35]
	s_add_u32 m0, s57, 0xe000
	s_add_u32 s46, s44, s40
	s_addc_u32 s47, s45, s41
	global_load_lds_dwordx4 v145, s[46:47]
	v_mfma_f32_16x16x32_bf16 v[28:31], v[182:185], v[206:209], v[28:31]
	v_mfma_f32_16x16x32_bf16 v[16:19], v[182:185], v[210:213], v[16:19]
	v_mfma_f32_16x16x32_bf16 v[24:27], v[182:185], v[214:217], v[24:27]
	v_mfma_f32_16x16x32_bf16 v[12:15], v[182:185], v[218:221], v[12:15]
	v_mfma_f32_16x16x32_bf16 v[4:7], v[186:189], v[206:209], v[4:7]
	v_mfma_f32_16x16x32_bf16 v[0:3], v[186:189], v[210:213], v[0:3]
	v_mfma_f32_16x16x32_bf16 v[20:23], v[186:189], v[214:217], v[20:23]
	v_mfma_f32_16x16x32_bf16 v[8:11], v[186:189], v[218:221], v[8:11]

.Lg11_top:
	s_waitcnt lgkmcnt(0)
	s_waitcnt vmcnt(0)
	s_barrier
	v_xor_b32_e32 v141, 0x10000, v141
	v_xor_b32_e32 v210, 0x10000, v210
	v_xor_b32_e32 v180, 0x10000, v180
	v_xor_b32_e32 v211, 0x10000, v211
	s_xor_b32 s45, s45, 0x10000
	ds_read_b128 v[142:145], v141
	ds_read_b128 v[146:149], v141 offset:2048
	ds_read_b128 v[150:153], v141 offset:4096
	ds_read_b128 v[154:157], v141 offset:6144
	ds_read_b128 v[174:177], v210 offset:32768
	ds_read_b128 v[182:185], v210 offset:34816
	ds_read_b128 v[186:189], v210 offset:36864
	ds_read_b128 v[190:193], v210 offset:38912
	v_mfma_f32_16x16x32_bf16 v[60:63], v[158:161], v[194:197], v[60:63]
	s_mov_b32 m0, s45
	s_add_u32 s38, s36, s12
	s_addc_u32 s39, s37, s13
	global_load_lds_dwordx4 v178, s[38:39]
	v_mfma_f32_16x16x32_bf16 v[56:59], v[158:161], v[198:201], v[56:59]
	s_add_u32 m0, s45, 0x2000
	s_add_u32 s38, s36, s14
	s_addc_u32 s39, s37, s15
	global_load_lds_dwordx4 v178, s[38:39]
	v_mfma_f32_16x16x32_bf16 v[52:55], v[158:161], v[202:205], v[52:55]
	s_add_u32 m0, s45, 0x4000
	s_add_u32 s38, s36, s16
	s_addc_u32 s39, s37, s17
	global_load_lds_dwordx4 v178, s[38:39]
	v_mfma_f32_16x16x32_bf16 v[48:51], v[158:161], v[206:209], v[48:51]
	s_add_u32 m0, s45, 0x6000
	s_add_u32 s38, s36, s18
	s_addc_u32 s39, s37, s19
	global_load_lds_dwordx4 v178, s[38:39]
	v_mfma_f32_16x16x32_bf16 v[44:47], v[162:165], v[194:197], v[44:47]
	s_add_u32 m0, s45, 0x8000
	s_add_u32 s38, s36, s22
	s_addc_u32 s39, s37, s23
	global_load_lds_dwordx4 v179, s[38:39]
	v_mfma_f32_16x16x32_bf16 v[32:35], v[162:165], v[198:201], v[32:35]
	s_add_u32 m0, s45, 0xa000
	s_add_u32 s38, s36, s24
	s_addc_u32 s39, s37, s25
	global_load_lds_dwordx4 v179, s[38:39]
	v_mfma_f32_16x16x32_bf16 v[28:31], v[162:165], v[202:205], v[28:31]
	s_add_u32 m0, s45, 0xc000
	s_add_u32 s38, s36, s26
	s_addc_u32 s39, s37, s27
	global_load_lds_dwordx4 v179, s[38:39]
	v_mfma_f32_16x16x32_bf16 v[24:27], v[162:165], v[206:209], v[24:27]
	s_add_u32 m0, s45, 0xe000
	s_add_u32 s38, s36, s28
	s_addc_u32 s39, s37, s29
	global_load_lds_dwordx4 v179, s[38:39]
	v_mfma_f32_16x16x32_bf16 v[20:23], v[166:169], v[194:197], v[20:23]
	v_mfma_f32_16x16x32_bf16 v[16:19], v[166:169], v[198:201], v[16:19]
	v_mfma_f32_16x16x32_bf16 v[12:15], v[166:169], v[202:205], v[12:15]
	v_mfma_f32_16x16x32_bf16 v[8:11], v[166:169], v[206:209], v[8:11]
	v_mfma_f32_16x16x32_bf16 v[4:7], v[170:173], v[194:197], v[4:7]
	v_mfma_f32_16x16x32_bf16 v[0:3], v[170:173], v[198:201], v[0:3]
	v_mfma_f32_16x16x32_bf16 v[40:43], v[170:173], v[202:205], v[40:43]
	v_mfma_f32_16x16x32_bf16 v[36:39], v[170:173], v[206:209], v[36:39]
